# v18 + workgroups with vcu%4==3 run decode/sample tasks first and the attention last
# baseline (speedup 1.0000x reference)
.LBB0_989:
	s_or_b64 exec, exec, s[4:5]
	s_and_b32 s52, s82, 3
	s_cmp_eq_u32 s52, 0
	s_cselect_b64 s[16:17], -1, 0
	s_abs_i32 s53, s33
	v_cvt_f32_u32_e32 v2, s53
	s_waitcnt vmcnt(0) lgkmcnt(0)
	s_barrier
	v_rcp_iflag_f32_e32 v2, v2
	s_memrealtime s[0:1]
	s_add_i32 s25, s33, 0xfff
	s_waitcnt lgkmcnt(0)
	s_sub_i32 s0, 0xfffff001, s33
	v_mul_f32_e32 v2, 0x4f7ffffe, v2
	v_cvt_u32_f32_e32 v2, v2
	s_max_i32 s54, s25, s0
	s_sub_i32 s0, 0, s53
	v_readfirstlane_b32 s28, v2
	s_mul_i32 s0, s0, s28
	s_mul_hi_u32 s0, s28, s0
	s_add_i32 s28, s28, s0
	s_add_i32 s0, s52, 1
	s_bitcmp1_b32 s0, 1
	s_cbranch_scc0 .LBB0_1072
	s_cmpk_gt_i32 s82, 0x3ff
	s_cbranch_scc1 .LBB0_1071
	s_cmp_lg_u32 0, -1
	s_cselect_b32 s0, 0, 0
	v_lshlrev_b32_e32 v6, 1, v0
	s_addk_i32 s0, 0x6000
	v_and_b32_e32 v5, 63, v0
	v_and_b32_e32 v223, 31, v0
	v_and_b32_e32 v6, 32, v6
	v_lshlrev_b32_e32 v10, 4, v0
	s_add_u32 s29, s26, 0x13200000
	v_bfe_u32 v7, v0, 5, 1
	v_mul_u32_u24_e32 v2, 0x600, v5
	v_lshlrev_b32_e32 v8, 3, v0
	v_add_u32_e32 v9, s0, v6
	v_and_b32_e32 v10, 0xc0, v10
	v_add_u32_e32 v13, 0, v6
	v_mul_u32_u24_e32 v6, 0x600, v223
	v_cmp_gt_u32_e64 s[4:5], 32, v5
	v_bfe_u32 v5, v0, 3, 3
	s_addc_u32 s38, s27, 0
	v_and_b32_e32 v4, 24, v8
	v_lshl_or_b32 v10, v7, 8, v10
	v_lshlrev_b32_e32 v11, 10, v7
	v_lshlrev_b32_e32 v12, 4, v223
	v_lshl_or_b32 v6, v7, 3, v6
	v_lshlrev_b32_e32 v244, 4, v7
	v_lshlrev_b32_e32 v245, 9, v7
	v_or_b32_e32 v7, 8, v5
	s_add_u32 s39, s26, 0x13200400
	v_add3_u32 v241, v9, v4, v10
	v_add3_u32 v242, 0, v11, v12
	v_add3_u32 v243, v13, v4, v10
	v_lshlrev_b32_e32 v246, 7, v5
	v_lshlrev_b32_e32 v10, 10, v5
	v_lshlrev_b32_e32 v247, 7, v7
	v_lshlrev_b32_e32 v12, 10, v7
	v_or_b32_e32 v7, 16, v5
	v_or_b32_e32 v5, 24, v5
	s_addc_u32 s40, s27, 0
	v_lshlrev_b32_e32 v249, 7, v5
	v_lshlrev_b32_e32 v16, 10, v5
	s_add_u32 s41, s26, 0x13200800
	v_lshlrev_b32_e32 v5, 2, v223
	s_addc_u32 s42, s27, 0
	v_sub_u32_e32 v5, v244, v5
	v_mov_b32_e32 v3, 0
	v_and_b32_e32 v8, 56, v8
	v_lshlrev_b32_e32 v14, 10, v7
	s_add_u32 s43, s26, 0x2e000000
	v_add_u32_e32 v5, 0, v5
	s_mov_b32 s18, 0xfffd0000
	v_bfe_u32 v240, v0, 2, 4
	s_mov_b32 s1, 0
	v_lshlrev_b32_e32 v248, 7, v7
	s_addc_u32 s44, s27, 0
	v_add_u32_e32 v250, 0x247fc, v5
	v_lshlrev_b32_e32 v224, 1, v2
	v_mov_b32_e32 v225, v3
	v_lshlrev_b32_e32 v226, 1, v4
	v_mov_b32_e32 v227, v3
	s_mov_b64 s[8:9], 0x30000
	v_lshlrev_b32_e32 v251, 1, v6
	v_mov_b32_e32 v18, v3
	v_mov_b32_e32 v19, v3
	v_mov_b32_e32 v20, v3
	v_mov_b32_e32 v21, v3
	v_mov_b32_e32 v22, v3
	v_mov_b32_e32 v23, v3
	v_mov_b32_e32 v24, v3
	v_mov_b32_e32 v25, v3
	v_mov_b32_e32 v26, v3
	v_mov_b32_e32 v27, v3
	v_mov_b32_e32 v28, v3
	v_mov_b32_e32 v29, v3
	v_mov_b32_e32 v30, v3
	v_mov_b32_e32 v31, v3
	v_mov_b32_e32 v32, v3
	v_mov_b32_e32 v33, v3
	s_mov_b64 s[10:11], 0x60000
	s_mov_b64 s[12:13], 0x90000
	s_mov_b64 s[14:15], 0xf0000
	s_mov_b32 s19, -1
	s_mov_b32 s45, 0x41000000
	v_lshlrev_b32_e32 v228, 1, v8
	v_lshlrev_b32_e32 v230, 1, v10
	v_lshlrev_b32_e32 v232, 1, v12
	v_lshlrev_b32_e32 v234, 1, v14
	v_lshlrev_b32_e32 v236, 1, v16
	v_mov_b32_e32 v254, 0x30000
	s_mov_b32 s46, s82
	s_branch .LBB0_993

.LBB0_1289:
	s_cmpk_gt_i32 s82, 0x3ff
	s_cselect_b64 s[0:1], -1, 0
	s_and_b32 s2, s82, 3
	s_add_i32 s2, s2, 1
	s_bitcmp1_b32 s2, 1
	s_cselect_b64 s[2:3], -1, 0
	s_or_b64 s[0:1], s[0:1], s[2:3]
	s_and_b64 vcc, exec, s[0:1]
	s_barrier
	s_cbranch_vccnz .LBB0_1370
	s_cmp_lg_u32 0, -1
	v_lshlrev_b32_e32 v6, 1, v0
	s_cselect_b32 s0, 0, 0
	v_and_b32_e32 v5, 63, v0
	v_and_b32_e32 v1, 31, v0
	v_and_b32_e32 v6, 32, v6
	s_addk_i32 s0, 0x6000
	v_lshlrev_b32_e32 v10, 4, v0
	v_bfe_u32 v7, v0, 5, 1
	v_mul_u32_u24_e32 v2, 0x600, v5
	v_lshlrev_b32_e32 v8, 3, v0
	v_add_u32_e32 v9, s0, v6
	v_and_b32_e32 v10, 0xc0, v10
	v_add_u32_e32 v13, 0, v6
	v_mul_u32_u24_e32 v6, 0x600, v1
	v_cmp_gt_u32_e64 s[2:3], 32, v5
	v_bfe_u32 v5, v0, 3, 3
	v_and_b32_e32 v4, 24, v8
	v_lshl_or_b32 v10, v7, 8, v10
	v_lshlrev_b32_e32 v11, 10, v7
	v_lshlrev_b32_e32 v12, 4, v1
	v_lshl_or_b32 v6, v7, 3, v6
	v_lshlrev_b32_e32 v242, 4, v7
	v_lshlrev_b32_e32 v243, 9, v7
	v_or_b32_e32 v7, 8, v5
	s_add_u32 s25, s26, 0x13200400
	v_add3_u32 v239, v9, v4, v10
	v_add3_u32 v240, 0, v11, v12
	v_add3_u32 v241, v13, v4, v10
	v_lshlrev_b32_e32 v244, 7, v5
	v_lshlrev_b32_e32 v10, 10, v5
	v_lshlrev_b32_e32 v245, 7, v7
	v_lshlrev_b32_e32 v12, 10, v7
	v_or_b32_e32 v7, 16, v5
	v_or_b32_e32 v5, 24, v5
	s_addc_u32 s28, s27, 0
	v_lshlrev_b32_e32 v247, 7, v5
	v_lshlrev_b32_e32 v16, 10, v5
	s_add_u32 s29, s26, 0x13200800
	v_lshlrev_b32_e32 v5, 2, v1
	s_addc_u32 s34, s27, 0
	v_sub_u32_e32 v5, v242, v5
	v_mov_b32_e32 v3, 0
	v_and_b32_e32 v8, 56, v8
	v_lshlrev_b32_e32 v14, 10, v7
	s_add_u32 s35, s26, 0x2e000000
	v_add_u32_e32 v5, 0, v5
	s_mov_b32 s14, 0xfffd0000
	v_bfe_u32 v238, v0, 2, 4
	s_mov_b32 s1, 0
	v_lshlrev_b32_e32 v246, 7, v7
	s_addc_u32 s36, s27, 0
	v_add_u32_e32 v248, 0x247fc, v5
	v_lshlrev_b32_e32 v222, 1, v2
	v_mov_b32_e32 v223, v3
	v_lshlrev_b32_e32 v224, 1, v4
	v_mov_b32_e32 v225, v3
	s_mov_b64 s[6:7], 0x30000
	v_lshlrev_b32_e32 v249, 1, v6
	v_mov_b32_e32 v18, v3
	v_mov_b32_e32 v19, v3
	v_mov_b32_e32 v20, v3
	v_mov_b32_e32 v21, v3
	v_mov_b32_e32 v22, v3
	v_mov_b32_e32 v23, v3
	v_mov_b32_e32 v24, v3
	v_mov_b32_e32 v25, v3
	v_mov_b32_e32 v26, v3
	v_mov_b32_e32 v27, v3
	v_mov_b32_e32 v28, v3
	v_mov_b32_e32 v29, v3
	v_mov_b32_e32 v30, v3
	v_mov_b32_e32 v31, v3
	v_mov_b32_e32 v32, v3
	v_mov_b32_e32 v33, v3
	s_mov_b64 s[8:9], 0x60000
	s_mov_b64 s[10:11], 0x90000
	s_mov_b64 s[12:13], 0xf0000
	s_mov_b32 s15, -1
	s_mov_b32 s37, 0x41000000
	v_lshlrev_b32_e32 v226, 1, v8
	v_lshlrev_b32_e32 v228, 1, v10
	v_lshlrev_b32_e32 v230, 1, v12
	v_lshlrev_b32_e32 v232, 1, v14
	v_lshlrev_b32_e32 v234, 1, v16
	v_mov_b32_e32 v250, 0x30000
	s_mov_b32 s38, s82
	s_branch .LBB0_1292
